# K fragments 1-2 requested ahead of the partner's P halves (P is needed late); first LDS requests of the step: V0 pair, K1, K2, P
# speedup vs baseline: 1.0073x; 1.0020x over previous
; #define SBAR() __builtin_amdgcn_sched_barrier(0)
; #define KDMA(k0, b) do { const char* g_ = (const char*)(Kh + (long)(k0) * DM); char* l_ = K_lds + (b) * 16384 + wu * 1024; \
;     DMA16(g_ + koff[0], l_); DMA16(g_ + koff[1], l_ + 8192); } while (0)
; #define VDMA(k0, b) do { const char* g_ = (const char*)(Vh + (long)(k0) * DM); char* l_ = V_lds + (b) * 32768 + wu * 1024; \
;     DMA16(g_ + voff[0], l_); DMA16(g_ + voff[1], l_ + 8192); DMA16(g_ + voff[0] + 256, l_ + 16384); DMA16(g_ + voff[1] + 256, l_ + 16384 + 8192); } while (0)
; #define VRD(D0, X) do { X##0 = tr_read<v_rd_off(D0, 0, 0)>(vb); X##1 = tr_read<v_rd_off(D0, 0, 1)>(vb); X##2 = tr_read<v_rd_off(D0, 1, 0)>(vb); X##3 = tr_read<v_rd_off(D0, 1, 1)>(vb); \
;     X##4 = tr_read<v_rd_off(D0, 2, 0)>(vb); X##5 = tr_read<v_rd_off(D0, 2, 1)>(vb); X##6 = tr_read<v_rd_off(D0, 3, 0)>(vb); X##7 = tr_read<v_rd_off(D0, 3, 1)>(vb); } while (0)
; template <int PROBE, int MODE>
; DI void dattn_body(const u16* __restrict__ Qb, const u16* __restrict__ Kh, const u16* __restrict__ Vh, u16* __restrict__ Ob, const u16* __restrict__ O1, float lam, const float* __restrict__ subg, int seq, int q0, float kmax2, char* lds) {
;     ...
;       if (j + 2 < NT) KDMA((j + 2) * KVBLK, j & 1);
;       if (more) VDMA((j + 1) * KVBLK, (j + 1) & 1);
;     }
;     bf16x8 kf[8];
;     if (more) { const char* Ks_ = K_lds + ((j + 1) & 1) * 16384;
; #pragma unroll
;       for (int d0 = 0; d0 < 8; ++d0) kf[d0] = *reinterpret_cast<const bf16x8*>(Ks_ + KSWZ(32 * kh + r32, (d0 * 16 + hi * 8) * 2)); }
;     const bf16x8 pb0 = *(const bf16x8*)(pr + (j & 1) * 16384), pb1 = *(const bf16x8*)(pr + (j & 1) * 16384 + 16);
;     const int vb = vb0 + (j & 1) * 32768;
;     s16x4 va0, va1, va2, va3, va4, va5, va6, va7, vc0, vc1, vc2, vc3, vc4, vc5, vc6, vc7;
;     VRD(0, va);
;     if (more) { asm volatile("s_waitcnt lgkmcnt(10)" ::: "memory"); SBAR();
;       if (!(PROBE & 4)) { S = f32x16{};
; #pragma unroll
;       for (int d0 = 0; d0 < 8; ++d0) S = __builtin_amdgcn_mfma_f32_32x32x16_bf16(kf[d0], qr[d0], S, 0, 0, 0); }
;       SBAR(); }
;     const bf16x8 A0 = kh ? pb0 : po0, A1 = kh ? pb1 : po1, A2 = kh ? po0 : pb0, A3 = kh ? po1 : pb1;
;     SMX_SETUP(j + 1)
;     ...
;     LWAIT(); VRD(1, vc); VMMP(0, va); SMXP(0);
;     LWAIT(); VRD(2, va); VMMP(1, vc); SMXP(1);
;     LWAIT(); VRD(3, vc); VMMP(2, va); SMXP(2);
;     LWAIT(); VMMP(3, vc); SMXP(3);
.Lfast0:
	s_sub_i32 s72, s18, 64
	s_and_b32 s101, s25, 0x4000
	s_addk_i32 s25, 0x4000
	s_and_b32 s19, s25, 0x4000
	s_and_b32 s48, s55, 1
	v_lshl_add_u32 v71, s48, 14, v210
	s_bfe_u32 s100, s85, 0x1000a
	s_lshl_b32 s100, s100, 13
	s_lshl_b32 s48, s48, 15
	s_sub_i32 s74, s48, s100
	s_add_i32 s48, s48, s100
	v_add_u32_e32 v216, s48, v212
	v_add_u32_e32 v233, s74, v212
	v_add_u32_e32 v68, s19, v213
	v_add_u32_e32 v64, v68, v198
	v_add_u32_e32 v69, v68, v199
	ds_read_b64_tr_b16 v[234:235], v216 offset:0
	ds_read_b64_tr_b16 v[236:237], v216 offset:0x800
	ds_read_b128 v[64:67], v64
	ds_read_b128 v[118:121], v69
	ds_read_b128 v[162:165], v71
	ds_read_b128 v[166:169], v71 offset:16
	v_add_u32_e32 v69, v68, v200
	v_add_u32_e32 v70, v68, v201
	ds_read_b128 v[122:125], v69
	ds_read_b128 v[126:129], v70
	ds_read_b64_tr_b16 v[238:239], v216 offset:0x1000
	ds_read_b64_tr_b16 v[240:241], v216 offset:0x1800
	v_add_u32_e32 v69, v68, v202
	v_add_u32_e32 v70, v68, v203
	ds_read_b128 v[134:137], v69
	ds_read_b128 v[138:141], v70
	v_add_u32_e32 v142, v68, v204
	v_add_u32_e32 v146, v68, v205
	s_cmp_gt_i32 s72, s87
	s_cselect_b32 s100, s21, s20
	v_sub_f32_e32 v160, s100, v158
	s_lshl_b32 s48, s72, 12
	s_add_u32 s48, s16, s48
	s_addc_u32 s49, s17, 0
	s_add_u32 s74, s48, 0x100
	s_addc_u32 s75, s49, 0
	s_and_b32 s100, s54, 0x8000
	s_add_i32 s100, s85, s100
	s_waitcnt lgkmcnt(10)
	v_mfma_f32_32x32x16_bf16 v[0:15], v[114:117], v[234:237], v[0:15]
	ds_read_b64_tr_b16 v[242:243], v233 offset:0x2000
	ds_read_b64_tr_b16 v[244:245], v233 offset:0x2800
	s_waitcnt lgkmcnt(11)
	v_mfma_f32_32x32x16_bf16 v[64:79], v[64:67], v[82:85], 0
	ds_read_b128 v[142:145], v142
	ds_read_b128 v[146:149], v146
	s_waitcnt lgkmcnt(12)
	v_mfma_f32_32x32x16_bf16 v[64:79], v[118:121], v[86:89], v[64:79]
	ds_read_b64_tr_b16 v[246:247], v233 offset:0x3000
	ds_read_b64_tr_b16 v[248:249], v233 offset:0x3800
	s_waitcnt lgkmcnt(11)
	v_mfma_f32_32x32x16_bf16 v[64:79], v[122:125], v[90:93], v[64:79]
	s_waitcnt lgkmcnt(10)
	v_mfma_f32_32x32x16_bf16 v[64:79], v[126:129], v[94:97], v[64:79]
	ds_read_b64_tr_b16 v[126:127], v233 offset:0x3200
	ds_read_b64_tr_b16 v[128:129], v233 offset:0x3a00
	s_waitcnt lgkmcnt(10)
	v_mfma_f32_32x32x16_bf16 v[0:15], v[130:133], v[238:241], v[0:15]
	s_mov_b32 m0, s100
	s_waitcnt lgkmcnt(9)
	v_mfma_f32_32x32x16_bf16 v[64:79], v[134:137], v[98:101], v[64:79]
	global_load_lds_dwordx4 v176, s[48:49]
	ds_read_b64_tr_b16 v[134:135], v233 offset:0x2200
	ds_read_b64_tr_b16 v[136:137], v233 offset:0x2a00
	s_add_i32 m0, s100, 0x2000
	s_waitcnt lgkmcnt(10)
	v_mfma_f32_32x32x16_bf16 v[64:79], v[138:141], v[102:105], v[64:79]
	global_load_lds_dwordx4 v156, s[48:49]
	ds_read_b64_tr_b16 v[138:139], v216 offset:0x200
	ds_read_b64_tr_b16 v[140:141], v216 offset:0xa00
	s_add_i32 m0, s100, 0x4000
	s_waitcnt lgkmcnt(10)
	v_mfma_f32_32x32x16_bf16 v[0:15], v[162:165], v[242:245], v[0:15]
	global_load_lds_dwordx4 v176, s[74:75]
	s_add_i32 m0, s100, 0x6000
	s_waitcnt lgkmcnt(9)
	v_mfma_f32_32x32x16_bf16 v[64:79], v[142:145], v[106:109], v[64:79]
	ds_read_b64_tr_b16 v[142:143], v216 offset:0x1200
	ds_read_b64_tr_b16 v[144:145], v216 offset:0x1a00
	s_waitcnt lgkmcnt(10)
	v_mfma_f32_32x32x16_bf16 v[64:79], v[146:149], v[110:113], v[64:79]
	global_load_lds_dwordx4 v156, s[74:75]
	s_waitcnt lgkmcnt(8)
	v_mfma_f32_32x32x16_bf16 v[0:15], v[166:169], v[246:249], v[0:15]
	s_add_i32 s48, s55, 2
	s_cmp_ge_u32 s48, s11
	s_cbranch_scc1 .Lfast0_k_done
	s_lshl_b32 s48, s18, 12
	s_add_u32 s48, s14, s48
	s_addc_u32 s49, s15, 0
	s_add_i32 s100, s82, s101
	s_mov_b32 m0, s100
	s_nop 0
	global_load_lds_dwordx4 v152, s[48:49]
	s_add_i32 m0, s100, 0x2000
	s_nop 0
	global_load_lds_dwordx4 v154, s[48:49]

; #define SBAR() __builtin_amdgcn_sched_barrier(0)
; #define KDMA(k0, b) do { const char* g_ = (const char*)(Kh + (long)(k0) * DM); char* l_ = K_lds + (b) * 16384 + wu * 1024; \
;     DMA16(g_ + koff[0], l_); DMA16(g_ + koff[1], l_ + 8192); } while (0)
; #define VDMA(k0, b) do { const char* g_ = (const char*)(Vh + (long)(k0) * DM); char* l_ = V_lds + (b) * 32768 + wu * 1024; \
;     DMA16(g_ + voff[0], l_); DMA16(g_ + voff[1], l_ + 8192); DMA16(g_ + voff[0] + 256, l_ + 16384); DMA16(g_ + voff[1] + 256, l_ + 16384 + 8192); } while (0)
; #define VRD(D0, X) do { X##0 = tr_read<v_rd_off(D0, 0, 0)>(vb); X##1 = tr_read<v_rd_off(D0, 0, 1)>(vb); X##2 = tr_read<v_rd_off(D0, 1, 0)>(vb); X##3 = tr_read<v_rd_off(D0, 1, 1)>(vb); \
;     X##4 = tr_read<v_rd_off(D0, 2, 0)>(vb); X##5 = tr_read<v_rd_off(D0, 2, 1)>(vb); X##6 = tr_read<v_rd_off(D0, 3, 0)>(vb); X##7 = tr_read<v_rd_off(D0, 3, 1)>(vb); } while (0)
; template <int PROBE, int MODE>
; DI void dattn_body(const u16* __restrict__ Qb, const u16* __restrict__ Kh, const u16* __restrict__ Vh, u16* __restrict__ Ob, const u16* __restrict__ O1, float lam, const float* __restrict__ subg, int seq, int q0, float kmax2, char* lds) {
;     ...
;       if (j + 2 < NT) KDMA((j + 2) * KVBLK, j & 1);
;       if (more) VDMA((j + 1) * KVBLK, (j + 1) & 1);
;     }
;     bf16x8 kf[8];
;     if (more) { const char* Ks_ = K_lds + ((j + 1) & 1) * 16384;
; #pragma unroll
;       for (int d0 = 0; d0 < 8; ++d0) kf[d0] = *reinterpret_cast<const bf16x8*>(Ks_ + KSWZ(32 * kh + r32, (d0 * 16 + hi * 8) * 2)); }
;     const bf16x8 pb0 = *(const bf16x8*)(pr + (j & 1) * 16384), pb1 = *(const bf16x8*)(pr + (j & 1) * 16384 + 16);
;     const int vb = vb0 + (j & 1) * 32768;
;     s16x4 va0, va1, va2, va3, va4, va5, va6, va7, vc0, vc1, vc2, vc3, vc4, vc5, vc6, vc7;
;     VRD(0, va);
;     if (more) { asm volatile("s_waitcnt lgkmcnt(10)" ::: "memory"); SBAR();
;       if (!(PROBE & 4)) { S = f32x16{};
; #pragma unroll
;       for (int d0 = 0; d0 < 8; ++d0) S = __builtin_amdgcn_mfma_f32_32x32x16_bf16(kf[d0], qr[d0], S, 0, 0, 0); }
;       SBAR(); }
;     const bf16x8 A0 = kh ? pb0 : po0, A1 = kh ? pb1 : po1, A2 = kh ? po0 : pb0, A3 = kh ? po1 : pb1;
;     SMX_SETUP(j + 1)
;     ...
;     LWAIT(); VRD(1, vc); VMMP(0, va); SMXP(0);
;     LWAIT(); VRD(2, va); VMMP(1, vc); SMXP(1);
;     LWAIT(); VRD(3, vc); VMMP(2, va); SMXP(2);
;     LWAIT(); VMMP(3, vc); SMXP(3);
.Lfast1:
	s_sub_i32 s72, s0, 64
	s_and_b32 s101, s24, 0x4000
	s_addk_i32 s24, 0x4000
	s_and_b32 s1, s24, 0x4000
	s_and_b32 s4, s40, 1
	v_lshl_add_u32 v71, s4, 14, v209
	s_bfe_u32 s100, s39, 0x1000a
	s_lshl_b32 s100, s100, 13
	s_lshl_b32 s4, s4, 15
	s_sub_i32 s18, s4, s100
	s_add_i32 s4, s4, s100
	v_add_u32_e32 v215, s4, v211
	v_add_u32_e32 v233, s18, v211
	v_add_u32_e32 v68, s1, v212
	v_add_u32_e32 v64, v68, v196
	v_add_u32_e32 v69, v68, v198
	ds_read_b64_tr_b16 v[234:235], v215 offset:0
	ds_read_b64_tr_b16 v[236:237], v215 offset:0x800
	ds_read_b128 v[64:67], v64
	ds_read_b128 v[118:121], v69
	ds_read_b128 v[162:165], v71
	ds_read_b128 v[166:169], v71 offset:16
	v_add_u32_e32 v69, v68, v199
	v_add_u32_e32 v70, v68, v200
	ds_read_b128 v[122:125], v69
	ds_read_b128 v[126:129], v70
	ds_read_b64_tr_b16 v[238:239], v215 offset:0x1000
	ds_read_b64_tr_b16 v[240:241], v215 offset:0x1800
	v_add_u32_e32 v69, v68, v201
	v_add_u32_e32 v70, v68, v202
	ds_read_b128 v[134:137], v69
	ds_read_b128 v[138:141], v70
	v_add_u32_e32 v142, v68, v203
	v_add_u32_e32 v146, v68, v204
	s_cmp_gt_i32 s72, s87
	s_cselect_b32 s100, s21, s20
	v_sub_f32_e32 v160, s100, v158
	s_lshl_b32 s4, s72, 12
	s_add_u32 s4, s16, s4
	s_addc_u32 s5, s17, 0
	s_add_u32 s18, s4, 0x100
	s_addc_u32 s19, s5, 0
	s_and_b32 s100, s25, 0x8000
	s_add_i32 s100, s39, s100
	s_waitcnt lgkmcnt(10)
	v_mfma_f32_32x32x16_bf16 v[0:15], v[114:117], v[234:237], v[0:15]
	ds_read_b64_tr_b16 v[242:243], v233 offset:0x2000
	ds_read_b64_tr_b16 v[244:245], v233 offset:0x2800
	s_waitcnt lgkmcnt(11)
	v_mfma_f32_32x32x16_bf16 v[64:79], v[64:67], v[82:85], 0
	ds_read_b128 v[142:145], v142
	ds_read_b128 v[146:149], v146
	s_waitcnt lgkmcnt(12)
	v_mfma_f32_32x32x16_bf16 v[64:79], v[118:121], v[86:89], v[64:79]
	ds_read_b64_tr_b16 v[246:247], v233 offset:0x3000
	ds_read_b64_tr_b16 v[248:249], v233 offset:0x3800
	s_waitcnt lgkmcnt(11)
	v_mfma_f32_32x32x16_bf16 v[64:79], v[122:125], v[90:93], v[64:79]
	s_waitcnt lgkmcnt(10)
	v_mfma_f32_32x32x16_bf16 v[64:79], v[126:129], v[94:97], v[64:79]
	ds_read_b64_tr_b16 v[126:127], v233 offset:0x3200
	ds_read_b64_tr_b16 v[128:129], v233 offset:0x3a00
	s_waitcnt lgkmcnt(10)
	v_mfma_f32_32x32x16_bf16 v[0:15], v[130:133], v[238:241], v[0:15]
	s_mov_b32 m0, s100
	s_waitcnt lgkmcnt(9)
	v_mfma_f32_32x32x16_bf16 v[64:79], v[134:137], v[98:101], v[64:79]
	global_load_lds_dwordx4 v152, s[4:5]
	ds_read_b64_tr_b16 v[134:135], v233 offset:0x2200
	ds_read_b64_tr_b16 v[136:137], v233 offset:0x2a00
	s_add_i32 m0, s100, 0x2000
	s_waitcnt lgkmcnt(10)
	v_mfma_f32_32x32x16_bf16 v[64:79], v[138:141], v[102:105], v[64:79]
	global_load_lds_dwordx4 v156, s[4:5]
	ds_read_b64_tr_b16 v[138:139], v215 offset:0x200
	ds_read_b64_tr_b16 v[140:141], v215 offset:0xa00
	s_add_i32 m0, s100, 0x4000
	s_waitcnt lgkmcnt(10)
	v_mfma_f32_32x32x16_bf16 v[0:15], v[162:165], v[242:245], v[0:15]
	global_load_lds_dwordx4 v152, s[18:19]
	s_add_i32 m0, s100, 0x6000
	s_waitcnt lgkmcnt(9)
	v_mfma_f32_32x32x16_bf16 v[64:79], v[142:145], v[106:109], v[64:79]
	ds_read_b64_tr_b16 v[142:143], v215 offset:0x1200
	ds_read_b64_tr_b16 v[144:145], v215 offset:0x1a00
	s_waitcnt lgkmcnt(10)
	v_mfma_f32_32x32x16_bf16 v[64:79], v[146:149], v[110:113], v[64:79]
	global_load_lds_dwordx4 v156, s[18:19]
	s_waitcnt lgkmcnt(8)
	v_mfma_f32_32x32x16_bf16 v[0:15], v[166:169], v[246:249], v[0:15]
	s_add_i32 s4, s40, 2
	s_cmp_ge_u32 s4, s11
	s_cbranch_scc1 .Lfast1_k_done
	s_lshl_b32 s4, s0, 12
	s_add_u32 s4, s14, s4
	s_addc_u32 s5, s15, 0
	s_add_u32 s4, s4, 0x100
	s_addc_u32 s5, s5, 0
	s_add_i32 s100, s38, s101
	s_mov_b32 m0, s100
	s_nop 0
	global_load_lds_dwordx4 v176, s[4:5]
	s_add_i32 m0, s100, 0x2000
	s_nop 0
	global_load_lds_dwordx4 v154, s[4:5]
